# GEMM 8-phase loop: the 16 per-phase s_setprio 1/0 flips deleted (timing-only change)
# speedup vs baseline: 1.0088x; 1.0030x over previous
; #define PG8_STAGE(bufoff, gbase, voff) do { _Pragma("unroll") for (int _i = 0; _i < 2; ++_i) \
;     __builtin_amdgcn_global_load_lds((const unsigned*)((const char*)(gbase) + (voff)[_i]), (LAS unsigned*)(lds + (bufoff) + ldsw + _i * 8192), 16, 0, 0); } while (0)
; #define PG8_LDA(dst, b, h) do { _Pragma("unroll") for (int m = 0; m < 4; ++m) _Pragma("unroll") for (int k = 0; k < 2; ++k) dst[m][k] = *(const LAS bf16x8*)(lds + PG8_SA(b, h) + aoff + m * 2048 + k * 1024); } while (0)
; #define PG8_LDB(dst, b, h) do { _Pragma("unroll") for (int n = 0; n < 2; ++n) _Pragma("unroll") for (int k = 0; k < 2; ++k) dst[n][k] = *(const LAS bf16x8*)(lds + PG8_SB(b, h) + boff + n * 2048 + k * 1024); } while (0)
; #define PG8_MMA(ai, bj, At, Bt) do { __builtin_amdgcn_s_setprio(1); _Pragma("unroll") for (int m = 0; m < 4; ++m) _Pragma("unroll") for (int n = 0; n < 2; ++n) _Pragma("unroll") for (int k = 0; k < 2; ++k) \
;     acc[ai][bj][m][n] = __builtin_amdgcn_mfma_f32_16x16x32_bf16(Bt[n][k], At[m][k], acc[ai][bj][m][n], 0, 0, 0); __builtin_amdgcn_s_setprio(0); } while (0)
; #define PG8_WAIT_L(n) asm volatile("s_waitcnt lgkmcnt(" #n ")" ::: "memory")
; #define PG8_BAR __builtin_amdgcn_s_barrier()
; #define PG8_SCHED __builtin_amdgcn_sched_barrier(0)
; template <class Epi>
; __device__ __forceinline__ void gemm_phase(LAS unsigned char* lds, const Gemm g, const Epi& E) {
;     ...
;       PG8_LDB(B0, 0, 0); PG8_SCHED; PG8_LDA(At, 0, 0); PG8_STAGE(PG8_SA(1, 1), a1 + hstepA, voffA);
;       PG8_WAIT_L(8); PG8_BAR; PG8_WAIT_L(0); PG8_MMA(0, 0, At, B0); PG8_BAR; PG8_SCHED;
;       PG8_LDB(B1, 0, 1); PG8_STAGE(PG8_SB(0, 0), b2, voffB);
;       PG8_BAR; PG8_WAIT_L(0); PG8_MMA(0, 1, At, B1); PG8_BAR;
;       PG8_LDA(At, 0, 1); PG8_STAGE(PG8_SA(0, 0), a2, voffA);
;       PG8_BAR; PG8_WAIT_L(0); PG8_MMA(1, 0, At, B0); PG8_BAR; PG8_SCHED;
.LBB0_579:
	s_add_i32 s76, s26, 2
	s_add_u32 s28, s2, 0x80
	s_addc_u32 s27, s3, 0
	s_add_i32 s83, 0, 0x10000
	v_add_u32_e32 v156, s83, v173
	ds_read_b128 v[128:131], v156
	ds_read_b128 v[148:151], v156 offset:1024
	ds_read_b128 v[152:155], v156 offset:2048
	ds_read_b128 v[156:159], v156 offset:3072
	s_cmp_eq_u32 s89, s26
	s_cselect_b32 s26, s0, s28
	s_cselect_b32 s27, s1, s27
	s_cselect_b32 s29, s21, s39
	s_cselect_b32 s28, s20, s38
	v_lshl_add_u64 v[196:197], s[2:3], 0, v[144:145]
	s_add_i32 m0, s84, 0xc000
	ds_read_b128 v[160:163], v175
	ds_read_b128 v[164:167], v175 offset:1024
	ds_read_b128 v[168:171], v175 offset:2048
	ds_read_b128 v[176:179], v175 offset:3072
	ds_read_b128 v[180:183], v175 offset:4096
	ds_read_b128 v[184:187], v175 offset:5120
	ds_read_b128 v[188:191], v175 offset:6144
	ds_read_b128 v[192:195], v175 offset:7168
	global_load_lds_dwordx4 v[196:197], off
	v_lshl_add_u64 v[196:197], s[2:3], 0, v[146:147]
	s_add_i32 m0, s84, 0xe000
	s_nop 0
	global_load_lds_dwordx4 v[196:197], off
	s_waitcnt lgkmcnt(8)
	s_barrier
	s_waitcnt lgkmcnt(0)
	s_waitcnt lgkmcnt(0)
	v_mfma_f32_16x16x32_bf16 v[124:127], v[128:131], v[160:163], v[124:127]
	v_mfma_f32_16x16x32_bf16 v[120:123], v[152:155], v[160:163], v[120:123]
	v_mfma_f32_16x16x32_bf16 v[108:111], v[128:131], v[168:171], v[108:111]
	v_mfma_f32_16x16x32_bf16 v[104:107], v[152:155], v[168:171], v[104:107]
	v_mfma_f32_16x16x32_bf16 v[92:95], v[128:131], v[180:183], v[92:95]
	v_mfma_f32_16x16x32_bf16 v[88:91], v[152:155], v[180:183], v[88:91]
	v_mfma_f32_16x16x32_bf16 v[76:79], v[128:131], v[188:191], v[76:79]
	v_mfma_f32_16x16x32_bf16 v[72:75], v[152:155], v[188:191], v[72:75]
	v_mfma_f32_16x16x32_bf16 v[124:127], v[148:151], v[164:167], v[124:127]
	v_mfma_f32_16x16x32_bf16 v[120:123], v[156:159], v[164:167], v[120:123]
	v_mfma_f32_16x16x32_bf16 v[108:111], v[148:151], v[176:179], v[108:111]
	v_mfma_f32_16x16x32_bf16 v[104:107], v[156:159], v[176:179], v[104:107]
	v_mfma_f32_16x16x32_bf16 v[92:95], v[148:151], v[184:187], v[92:95]
	v_mfma_f32_16x16x32_bf16 v[88:91], v[156:159], v[184:187], v[88:91]
	v_mfma_f32_16x16x32_bf16 v[76:79], v[148:151], v[192:195], v[76:79]
	v_mfma_f32_16x16x32_bf16 v[72:75], v[156:159], v[192:195], v[72:75]
	s_barrier
	s_add_i32 s94, 0, 0x14000
	s_add_i32 s83, s83, s97
	v_add_u32_e32 v208, s94, v173
	v_lshl_add_u64 v[212:213], s[28:29], 0, v[132:133]
	s_mov_b32 m0, s83
	ds_read_b128 v[196:199], v208
	ds_read_b128 v[200:203], v208 offset:1024
	ds_read_b128 v[204:207], v208 offset:2048
	ds_read_b128 v[208:211], v208 offset:3072
	global_load_lds_dwordx4 v[212:213], off
	v_lshl_add_u64 v[214:215], s[28:29], 0, v[142:143]
	s_add_i32 m0, s83, 0x2000
	s_nop 0
	global_load_lds_dwordx4 v[214:215], off
	s_barrier
	s_waitcnt lgkmcnt(0)
	s_waitcnt lgkmcnt(0)
	v_mfma_f32_16x16x32_bf16 v[116:119], v[196:199], v[160:163], v[116:119]
	v_mfma_f32_16x16x32_bf16 v[112:115], v[204:207], v[160:163], v[112:115]
	v_mfma_f32_16x16x32_bf16 v[100:103], v[196:199], v[168:171], v[100:103]
	v_mfma_f32_16x16x32_bf16 v[96:99], v[204:207], v[168:171], v[96:99]
	v_mfma_f32_16x16x32_bf16 v[84:87], v[196:199], v[180:183], v[84:87]
	v_mfma_f32_16x16x32_bf16 v[80:83], v[204:207], v[180:183], v[80:83]
	v_mfma_f32_16x16x32_bf16 v[68:71], v[196:199], v[188:191], v[68:71]
	v_mfma_f32_16x16x32_bf16 v[64:67], v[204:207], v[188:191], v[64:67]
	v_mfma_f32_16x16x32_bf16 v[116:119], v[200:203], v[164:167], v[116:119]
	v_mfma_f32_16x16x32_bf16 v[112:115], v[208:211], v[164:167], v[112:115]
	v_mfma_f32_16x16x32_bf16 v[100:103], v[200:203], v[176:179], v[100:103]
	v_mfma_f32_16x16x32_bf16 v[96:99], v[208:211], v[176:179], v[96:99]
	v_mfma_f32_16x16x32_bf16 v[84:87], v[200:203], v[184:187], v[84:87]
	v_mfma_f32_16x16x32_bf16 v[80:83], v[208:211], v[184:187], v[80:83]
	v_mfma_f32_16x16x32_bf16 v[68:71], v[200:203], v[192:195], v[68:71]
	v_mfma_f32_16x16x32_bf16 v[64:67], v[208:211], v[192:195], v[64:67]
	s_mov_b32 m0, s84
	v_lshl_add_u64 v[216:217], s[26:27], 0, v[138:139]
	s_barrier
	ds_read_b128 v[160:163], v175 offset:16384
	ds_read_b128 v[164:167], v175 offset:17408
	ds_read_b128 v[168:171], v175 offset:18432
	ds_read_b128 v[176:179], v175 offset:19456
	ds_read_b128 v[180:183], v175 offset:20480
	ds_read_b128 v[184:187], v175 offset:21504
	ds_read_b128 v[188:191], v175 offset:22528
	ds_read_b128 v[192:195], v175 offset:23552
	global_load_lds_dwordx4 v[216:217], off
	v_lshl_add_u64 v[218:219], s[26:27], 0, v[140:141]
	s_mov_b32 m0, s85
	s_nop 0
	global_load_lds_dwordx4 v[218:219], off
	s_barrier
	s_waitcnt lgkmcnt(0)
	s_waitcnt lgkmcnt(0)
	v_mfma_f32_16x16x32_bf16 v[60:63], v[128:131], v[160:163], v[60:63]
	v_mfma_f32_16x16x32_bf16 v[56:59], v[152:155], v[160:163], v[56:59]
	v_mfma_f32_16x16x32_bf16 v[44:47], v[128:131], v[168:171], v[44:47]
	v_mfma_f32_16x16x32_bf16 v[40:43], v[152:155], v[168:171], v[40:43]
	v_mfma_f32_16x16x32_bf16 v[28:31], v[128:131], v[180:183], v[28:31]
	v_mfma_f32_16x16x32_bf16 v[24:27], v[152:155], v[180:183], v[24:27]
	v_mfma_f32_16x16x32_bf16 v[12:15], v[128:131], v[188:191], v[12:15]
	v_mfma_f32_16x16x32_bf16 v[8:11], v[152:155], v[188:191], v[8:11]
	v_mfma_f32_16x16x32_bf16 v[60:63], v[148:151], v[164:167], v[60:63]
	v_mfma_f32_16x16x32_bf16 v[56:59], v[156:159], v[164:167], v[56:59]
	v_mfma_f32_16x16x32_bf16 v[44:47], v[148:151], v[176:179], v[44:47]
	v_mfma_f32_16x16x32_bf16 v[40:43], v[156:159], v[176:179], v[40:43]
	v_mfma_f32_16x16x32_bf16 v[28:31], v[148:151], v[184:187], v[28:31]
	v_mfma_f32_16x16x32_bf16 v[24:27], v[156:159], v[184:187], v[24:27]
	v_mfma_f32_16x16x32_bf16 v[12:15], v[148:151], v[192:195], v[12:15]
	v_mfma_f32_16x16x32_bf16 v[8:11], v[156:159], v[192:195], v[8:11]
	s_barrier
; #define PG8_STAGE(bufoff, gbase, voff) do { _Pragma("unroll") for (int _i = 0; _i < 2; ++_i) \
;     __builtin_amdgcn_global_load_lds((const unsigned*)((const char*)(gbase) + (voff)[_i]), (LAS unsigned*)(lds + (bufoff) + ldsw + _i * 8192), 16, 0, 0); } while (0)
; #define PG8_LDA(dst, b, h) do { _Pragma("unroll") for (int m = 0; m < 4; ++m) _Pragma("unroll") for (int k = 0; k < 2; ++k) dst[m][k] = *(const LAS bf16x8*)(lds + PG8_SA(b, h) + aoff + m * 2048 + k * 1024); } while (0)
; #define PG8_LDB(dst, b, h) do { _Pragma("unroll") for (int n = 0; n < 2; ++n) _Pragma("unroll") for (int k = 0; k < 2; ++k) dst[n][k] = *(const LAS bf16x8*)(lds + PG8_SB(b, h) + boff + n * 2048 + k * 1024); } while (0)
; #define PG8_MMA(ai, bj, At, Bt) do { __builtin_amdgcn_s_setprio(1); _Pragma("unroll") for (int m = 0; m < 4; ++m) _Pragma("unroll") for (int n = 0; n < 2; ++n) _Pragma("unroll") for (int k = 0; k < 2; ++k) \
;     acc[ai][bj][m][n] = __builtin_amdgcn_mfma_f32_16x16x32_bf16(Bt[n][k], At[m][k], acc[ai][bj][m][n], 0, 0, 0); __builtin_amdgcn_s_setprio(0); } while (0)
; #define PG8_WAIT_V(n) asm volatile("s_waitcnt vmcnt(" #n ")" ::: "memory")
; #define PG8_WAIT_L(n) asm volatile("s_waitcnt lgkmcnt(" #n ")" ::: "memory")
; #define PG8_BAR __builtin_amdgcn_s_barrier()
; #define PG8_SCHED __builtin_amdgcn_sched_barrier(0)
; template <class Epi>
; __device__ __forceinline__ void gemm_phase(LAS unsigned char* lds, const Gemm g, const Epi& E) {
;     ...
;       PG8_STAGE(PG8_SB(0, 1), b2 + hstepB, voffB);
;       PG8_WAIT_V(6); PG8_BAR; PG8_MMA(1, 1, At, B1); PG8_BAR;
;       PG8_LDB(B0, 1, 0); PG8_SCHED; PG8_LDA(At, 1, 0); PG8_STAGE(PG8_SA(0, 1), a2 + hstepA, voffA);
;       PG8_WAIT_L(8); PG8_BAR; PG8_WAIT_L(0); PG8_MMA(0, 0, At, B0); PG8_BAR; PG8_SCHED;
;       PG8_LDB(B1, 1, 1); PG8_STAGE(PG8_SB(1, 0), b3, voffB);
;       PG8_BAR; PG8_WAIT_L(0); PG8_MMA(0, 1, At, B1); PG8_BAR;
	s_add_u32 s28, s28, s95
	s_addc_u32 s29, s29, 0
	s_add_i32 s83, s94, s97
	v_lshl_add_u64 v[220:221], s[28:29], 0, v[132:133]
	s_mov_b32 m0, s83
	v_lshl_add_u64 v[222:223], s[28:29], 0, v[142:143]
	global_load_lds_dwordx4 v[220:221], off
	s_add_i32 m0, s83, 0x2000
	s_nop 0
	global_load_lds_dwordx4 v[222:223], off
	s_waitcnt vmcnt(6)
	s_barrier
	v_mfma_f32_16x16x32_bf16 v[52:55], v[196:199], v[160:163], v[52:55]
	v_mfma_f32_16x16x32_bf16 v[48:51], v[204:207], v[160:163], v[48:51]
	v_mfma_f32_16x16x32_bf16 v[36:39], v[196:199], v[168:171], v[36:39]
	v_mfma_f32_16x16x32_bf16 v[32:35], v[204:207], v[168:171], v[32:35]
	v_mfma_f32_16x16x32_bf16 v[20:23], v[196:199], v[180:183], v[20:23]
	v_mfma_f32_16x16x32_bf16 v[16:19], v[204:207], v[180:183], v[16:19]
	v_mfma_f32_16x16x32_bf16 v[4:7], v[196:199], v[188:191], v[4:7]
	v_mfma_f32_16x16x32_bf16 v[0:3], v[204:207], v[188:191], v[0:3]
	v_mfma_f32_16x16x32_bf16 v[52:55], v[200:203], v[164:167], v[52:55]
	v_mfma_f32_16x16x32_bf16 v[48:51], v[208:211], v[164:167], v[48:51]
	v_mfma_f32_16x16x32_bf16 v[36:39], v[200:203], v[176:179], v[36:39]
	v_mfma_f32_16x16x32_bf16 v[32:35], v[208:211], v[176:179], v[32:35]
	v_mfma_f32_16x16x32_bf16 v[20:23], v[200:203], v[184:187], v[20:23]
	v_mfma_f32_16x16x32_bf16 v[16:19], v[208:211], v[184:187], v[16:19]
	v_mfma_f32_16x16x32_bf16 v[4:7], v[200:203], v[192:195], v[4:7]
	v_mfma_f32_16x16x32_bf16 v[0:3], v[208:211], v[192:195], v[0:3]
	s_add_i32 s28, 0, 0x18000
	v_add_u32_e32 v156, s28, v173
	s_barrier
	ds_read_b128 v[128:131], v156
	ds_read_b128 v[148:151], v156 offset:1024
	ds_read_b128 v[152:155], v156 offset:2048
	ds_read_b128 v[156:159], v156 offset:3072
	s_add_u32 s26, s26, s56
	s_addc_u32 s27, s27, 0
	s_mov_b32 m0, s86
	v_lshl_add_u64 v[196:197], s[26:27], 0, v[138:139]
	ds_read_b128 v[160:163], v175 offset:32768
	ds_read_b128 v[164:167], v175 offset:33792
	ds_read_b128 v[168:171], v175 offset:34816
	ds_read_b128 v[176:179], v175 offset:35840
	ds_read_b128 v[180:183], v175 offset:36864
	ds_read_b128 v[184:187], v175 offset:37888
	ds_read_b128 v[188:191], v175 offset:38912
	ds_read_b128 v[192:195], v175 offset:39936
	global_load_lds_dwordx4 v[196:197], off
	v_lshl_add_u64 v[196:197], s[26:27], 0, v[140:141]
	s_mov_b32 m0, s87
	s_nop 0
	global_load_lds_dwordx4 v[196:197], off
	s_waitcnt lgkmcnt(8)
	s_barrier
	s_waitcnt lgkmcnt(0)
	s_waitcnt lgkmcnt(0)
	v_mfma_f32_16x16x32_bf16 v[124:127], v[128:131], v[160:163], v[124:127]
	v_mfma_f32_16x16x32_bf16 v[120:123], v[152:155], v[160:163], v[120:123]
	v_mfma_f32_16x16x32_bf16 v[108:111], v[128:131], v[168:171], v[108:111]
	v_mfma_f32_16x16x32_bf16 v[104:107], v[152:155], v[168:171], v[104:107]
	v_mfma_f32_16x16x32_bf16 v[92:95], v[128:131], v[180:183], v[92:95]
	v_mfma_f32_16x16x32_bf16 v[88:91], v[152:155], v[180:183], v[88:91]
	v_mfma_f32_16x16x32_bf16 v[76:79], v[128:131], v[188:191], v[76:79]
	v_mfma_f32_16x16x32_bf16 v[72:75], v[152:155], v[188:191], v[72:75]
	v_mfma_f32_16x16x32_bf16 v[124:127], v[148:151], v[164:167], v[124:127]
	v_mfma_f32_16x16x32_bf16 v[120:123], v[156:159], v[164:167], v[120:123]
	v_mfma_f32_16x16x32_bf16 v[108:111], v[148:151], v[176:179], v[108:111]
	v_mfma_f32_16x16x32_bf16 v[104:107], v[156:159], v[176:179], v[104:107]
	v_mfma_f32_16x16x32_bf16 v[92:95], v[148:151], v[184:187], v[92:95]
	v_mfma_f32_16x16x32_bf16 v[88:91], v[156:159], v[184:187], v[88:91]
	v_mfma_f32_16x16x32_bf16 v[76:79], v[148:151], v[192:195], v[76:79]
	v_mfma_f32_16x16x32_bf16 v[72:75], v[156:159], v[192:195], v[72:75]
	s_barrier
	s_add_i32 s26, 0, 0x1c000
	s_add_i32 s27, s28, s97
	v_add_u32_e32 v208, s26, v173
	v_lshl_add_u64 v[212:213], v[212:213], 0, s[22:23]
	s_mov_b32 m0, s27
	ds_read_b128 v[196:199], v208
	ds_read_b128 v[200:203], v208 offset:1024
	ds_read_b128 v[204:207], v208 offset:2048
	ds_read_b128 v[208:211], v208 offset:3072
	global_load_lds_dwordx4 v[212:213], off
	v_lshl_add_u64 v[212:213], v[214:215], 0, s[22:23]
	s_add_i32 m0, s27, 0x2000
	s_nop 0
	global_load_lds_dwordx4 v[212:213], off
	s_barrier
	s_waitcnt lgkmcnt(0)
	s_waitcnt lgkmcnt(0)
	v_mfma_f32_16x16x32_bf16 v[116:119], v[196:199], v[160:163], v[116:119]
	v_mfma_f32_16x16x32_bf16 v[112:115], v[204:207], v[160:163], v[112:115]
	v_mfma_f32_16x16x32_bf16 v[100:103], v[196:199], v[168:171], v[100:103]
	v_mfma_f32_16x16x32_bf16 v[96:99], v[204:207], v[168:171], v[96:99]
	v_mfma_f32_16x16x32_bf16 v[84:87], v[196:199], v[180:183], v[84:87]
	v_mfma_f32_16x16x32_bf16 v[80:83], v[204:207], v[180:183], v[80:83]
	v_mfma_f32_16x16x32_bf16 v[68:71], v[196:199], v[188:191], v[68:71]
	v_mfma_f32_16x16x32_bf16 v[64:67], v[204:207], v[188:191], v[64:67]
	v_mfma_f32_16x16x32_bf16 v[116:119], v[200:203], v[164:167], v[116:119]
	v_mfma_f32_16x16x32_bf16 v[112:115], v[208:211], v[164:167], v[112:115]
	v_mfma_f32_16x16x32_bf16 v[100:103], v[200:203], v[176:179], v[100:103]
	v_mfma_f32_16x16x32_bf16 v[96:99], v[208:211], v[176:179], v[96:99]
	v_mfma_f32_16x16x32_bf16 v[84:87], v[200:203], v[184:187], v[84:87]
	v_mfma_f32_16x16x32_bf16 v[80:83], v[208:211], v[184:187], v[80:83]
	v_mfma_f32_16x16x32_bf16 v[68:71], v[200:203], v[192:195], v[68:71]
	v_mfma_f32_16x16x32_bf16 v[64:67], v[208:211], v[192:195], v[64:67]
	s_mov_b32 m0, s74
	v_lshl_add_u64 v[212:213], v[216:217], 0, s[22:23]
	s_barrier
; #define PG8_STAGE(bufoff, gbase, voff) do { _Pragma("unroll") for (int _i = 0; _i < 2; ++_i) \
;     __builtin_amdgcn_global_load_lds((const unsigned*)((const char*)(gbase) + (voff)[_i]), (LAS unsigned*)(lds + (bufoff) + ldsw + _i * 8192), 16, 0, 0); } while (0)
; #define PG8_LDA(dst, b, h) do { _Pragma("unroll") for (int m = 0; m < 4; ++m) _Pragma("unroll") for (int k = 0; k < 2; ++k) dst[m][k] = *(const LAS bf16x8*)(lds + PG8_SA(b, h) + aoff + m * 2048 + k * 1024); } while (0)
; #define PG8_MMA(ai, bj, At, Bt) do { __builtin_amdgcn_s_setprio(1); _Pragma("unroll") for (int m = 0; m < 4; ++m) _Pragma("unroll") for (int n = 0; n < 2; ++n) _Pragma("unroll") for (int k = 0; k < 2; ++k) \
;     acc[ai][bj][m][n] = __builtin_amdgcn_mfma_f32_16x16x32_bf16(Bt[n][k], At[m][k], acc[ai][bj][m][n], 0, 0, 0); __builtin_amdgcn_s_setprio(0); } while (0)
; #define PG8_WAIT_V(n) asm volatile("s_waitcnt vmcnt(" #n ")" ::: "memory")
; #define PG8_WAIT_L(n) asm volatile("s_waitcnt lgkmcnt(" #n ")" ::: "memory")
; #define PG8_BAR __builtin_amdgcn_s_barrier()
; #define PG8_SCHED __builtin_amdgcn_sched_barrier(0)
; template <class Epi>
; __device__ __forceinline__ void gemm_phase(LAS unsigned char* lds, const Gemm g, const Epi& E) {
;     ...
;       PG8_LDA(At, 1, 1); PG8_STAGE(PG8_SA(1, 0), a3, voffA);
;       PG8_BAR; PG8_WAIT_L(0); PG8_MMA(1, 0, At, B0); PG8_BAR; PG8_SCHED;
;       PG8_STAGE(PG8_SB(1, 1), b3 + hstepB, voffB);
;       PG8_WAIT_V(6); PG8_BAR; PG8_MMA(1, 1, At, B1); PG8_BAR;
;     }
;     {
; #pragma unroll
;       for (int ai = 0; ai < 2; ++ai)
; #pragma unroll
;         for (int m = 0; m < 4; ++m)
; #pragma unroll
;           for (int bj = 0; bj < 2; ++bj)
;           { E.st2(cur.w, cur.pm * BM + ai * HALF + wr * 64 + m * 16 + fr, cur.pn * BM + bj * HALF + wc * 32 + 8 * fq, acc[ai][bj][m][0], acc[ai][bj][m][1]); if (bj == 1 && (m & 1)) asm volatile("" ::: "memory"); }
	ds_read_b128 v[160:163], v175 offset:49152
	ds_read_b128 v[164:167], v175 offset:50176
	ds_read_b128 v[168:171], v175 offset:51200
	ds_read_b128 v[176:179], v175 offset:52224
	ds_read_b128 v[180:183], v175 offset:53248
	ds_read_b128 v[184:187], v175 offset:54272
	ds_read_b128 v[188:191], v175 offset:55296
	ds_read_b128 v[192:195], v175 offset:56320
	global_load_lds_dwordx4 v[212:213], off
	v_lshl_add_u64 v[212:213], v[218:219], 0, s[22:23]
	s_mov_b32 m0, s78
	s_nop 0
	global_load_lds_dwordx4 v[212:213], off
	s_barrier
	s_waitcnt lgkmcnt(0)
	s_waitcnt lgkmcnt(0)
	v_mfma_f32_16x16x32_bf16 v[60:63], v[128:131], v[160:163], v[60:63]
	v_mfma_f32_16x16x32_bf16 v[56:59], v[152:155], v[160:163], v[56:59]
	v_mfma_f32_16x16x32_bf16 v[44:47], v[128:131], v[168:171], v[44:47]
	v_mfma_f32_16x16x32_bf16 v[40:43], v[152:155], v[168:171], v[40:43]
	v_mfma_f32_16x16x32_bf16 v[28:31], v[128:131], v[180:183], v[28:31]
	v_mfma_f32_16x16x32_bf16 v[24:27], v[152:155], v[180:183], v[24:27]
	v_mfma_f32_16x16x32_bf16 v[12:15], v[128:131], v[188:191], v[12:15]
	v_mfma_f32_16x16x32_bf16 v[8:11], v[152:155], v[188:191], v[8:11]
	v_mfma_f32_16x16x32_bf16 v[60:63], v[148:151], v[164:167], v[60:63]
	v_mfma_f32_16x16x32_bf16 v[56:59], v[156:159], v[164:167], v[56:59]
	v_mfma_f32_16x16x32_bf16 v[44:47], v[148:151], v[176:179], v[44:47]
	v_mfma_f32_16x16x32_bf16 v[40:43], v[156:159], v[176:179], v[40:43]
	v_mfma_f32_16x16x32_bf16 v[28:31], v[148:151], v[184:187], v[28:31]
	v_mfma_f32_16x16x32_bf16 v[24:27], v[156:159], v[184:187], v[24:27]
	v_mfma_f32_16x16x32_bf16 v[12:15], v[148:151], v[192:195], v[12:15]
	v_mfma_f32_16x16x32_bf16 v[8:11], v[156:159], v[192:195], v[8:11]
	s_barrier
	s_add_i32 s26, s26, s97
	v_lshl_add_u64 v[128:129], v[220:221], 0, s[22:23]
	s_mov_b32 m0, s26
	s_nop 0
	global_load_lds_dwordx4 v[128:129], off
	v_lshl_add_u64 v[128:129], v[222:223], 0, s[22:23]
	s_add_i32 m0, s26, 0x2000
	s_nop 0
	global_load_lds_dwordx4 v[128:129], off
	s_waitcnt vmcnt(6)
	s_barrier
	v_mfma_f32_16x16x32_bf16 v[52:55], v[196:199], v[160:163], v[52:55]
	v_mfma_f32_16x16x32_bf16 v[48:51], v[204:207], v[160:163], v[48:51]
	v_mfma_f32_16x16x32_bf16 v[36:39], v[196:199], v[168:171], v[36:39]
	v_mfma_f32_16x16x32_bf16 v[32:35], v[204:207], v[168:171], v[32:35]
	v_mfma_f32_16x16x32_bf16 v[20:23], v[196:199], v[180:183], v[20:23]
	v_mfma_f32_16x16x32_bf16 v[16:19], v[204:207], v[180:183], v[16:19]
	v_mfma_f32_16x16x32_bf16 v[4:7], v[196:199], v[188:191], v[4:7]
	v_mfma_f32_16x16x32_bf16 v[0:3], v[204:207], v[188:191], v[0:3]
	v_mfma_f32_16x16x32_bf16 v[52:55], v[200:203], v[164:167], v[52:55]
	v_mfma_f32_16x16x32_bf16 v[48:51], v[208:211], v[164:167], v[48:51]
	v_mfma_f32_16x16x32_bf16 v[36:39], v[200:203], v[176:179], v[36:39]
	v_mfma_f32_16x16x32_bf16 v[32:35], v[208:211], v[176:179], v[32:35]
	v_mfma_f32_16x16x32_bf16 v[20:23], v[200:203], v[184:187], v[20:23]
	v_mfma_f32_16x16x32_bf16 v[16:19], v[208:211], v[184:187], v[16:19]
	v_mfma_f32_16x16x32_bf16 v[4:7], v[200:203], v[192:195], v[4:7]
	v_mfma_f32_16x16x32_bf16 v[0:3], v[208:211], v[192:195], v[0:3]
	s_add_u32 s2, s2, 0x100
	s_addc_u32 s3, s3, 0
	s_add_u32 s38, s38, 0x100
	s_addc_u32 s39, s39, 0
	s_cmp_ge_u32 s76, s72
	s_mov_b32 s26, s76
	s_barrier
	s_cbranch_scc0 .LBB0_579
	s_lshl_b32 s28, s53, 8
	v_lshl_add_u32 v150, s75, 8, v172
	s_cmp_eq_u32 s12, 0
	v_ashrrev_i32_e32 v151, 31, v150
	v_mad_i64_i32 v[164:165], s[2:3], v150, s54, 0
	v_mad_i64_i32 v[154:155], s[2:3], v150, s33, 0
	s_cselect_b32 s29, s40, s41
	v_lshlrev_b64 v[162:163], 10, v[150:151]
	v_cmp_gt_i32_e64 s[38:39], s92, v150
	v_lshlrev_b64 v[152:153], 12, v[150:151]
	v_or_b32_e32 v148, s28, v174
	s_cmp_lt_i32 s29, 4
	s_mov_b64 s[2:3], -1
	s_cbranch_scc1 .LBB0_593
	s_cmp_lt_i32 s29, 6
	s_cbranch_scc1 .LBB0_587
	s_cmp_gt_i32 s29, 6
	s_cbranch_scc0 .LBB0_584
	v_lshl_add_u64 v[128:129], s[58:59], 0, v[152:153]
	v_ashrrev_i32_e32 v149, 31, v148
	v_lshl_add_u64 v[160:161], v[148:149], 2, v[128:129]
	global_load_dwordx4 v[128:131], v[160:161], off nt
	global_load_dwordx4 v[156:159], v[160:161], off offset:16 nt
	s_mov_b64 s[2:3], 0
	s_waitcnt vmcnt(0)
	v_pk_add_f32 v[130:131], v[126:127], v[130:131]
	v_pk_add_f32 v[128:129], v[124:125], v[128:129]
	v_pk_add_f32 v[158:159], v[122:123], v[158:159]
	v_pk_add_f32 v[156:157], v[120:121], v[156:157]
	global_store_dwordx4 v[160:161], v[128:131], off nt
	global_store_dwordx4 v[160:161], v[156:159], off offset:16 nt
